# attention B: pipelined V fragment reads in PV, O-rescale packed muls unpacked, lean bias path for unmasked bucket-crossing tiles
# speedup vs baseline: 1.0239x; 1.0239x over previous
; __device__ __forceinline__ f32x4 mfma16(bf16x8 a, bf16x8 b, f32x4 c) { return __builtin_amdgcn_mfma_f32_16x16x32_bf16(a, b, c, 0, 0, 0); }
; template <int DQK, int DV, int MODE> ...
;     ...
;         for (int t = 0; t < 4; ++t) {
;           {
;             const bf16x8 kf = *(const bf16x8*)(Ks + (t * 16 + fr) * KST + fq * 8);
; #pragma unroll
;             for (int qq = 0; qq < QG; ++qq) S[qq][t] = __builtin_amdgcn_mfma_f32_16x16x32_bf16(kf, *(const bf16x8*)(Qs2 + ((q0 + qq) * NKS) * 512), (f32x4){0.f, 0.f, 0.f, 0.f}, 0, 0, 0);
;           }
; #pragma unroll
;           for (int ks = 1; ks < NKS; ++ks) {
;             const bf16x8 kf = *(const bf16x8*)(Ks + (t * 16 + fr) * KST + ks * 32 + fq * 8);
; #pragma unroll
;             for (int qq = 0; qq < QG; ++qq) S[qq][t] = mfma16(kf, *(const bf16x8*)(Qs2 + ((q0 + qq) * NKS + ks) * 512), S[qq][t]);
;           }
;         }
;     ...
;                 const int j = kt * 64 + t * 16 + fq * 4 + r;
;                 float sx = S[qq][t][r] * c1;
;                 if (MODE == 1) {
;                   const int dist = qpos0 + qrow - j;
;                   sx += bias_lds[min(max(dist, 0), 2047)];
;                   if (need_mask && dist < 0) sx = -1e30f;
.LBB0_538:
	s_or_b64 exec, exec, s[4:5]
	ds_read_b128 v[114:117], v90
	ds_read_b128 v[170:173], v90 offset:1024
	ds_read_b128 v[166:169], v90 offset:2048
	ds_read_b128 v[174:177], v90 offset:3072
	ds_read_b128 v[92:95], v207
	ds_read_b128 v[102:105], v207 offset:64
	s_xor_b64 s[4:5], s[12:13], -1
	v_cmp_gt_i32_e32 vcc, s26, v226
	s_waitcnt lgkmcnt(0)
	v_mfma_f32_16x16x32_bf16 v[96:99], v[92:95], v[114:117], 0
	ds_read_b128 v[178:181], v207 offset:5184
	v_mfma_f32_16x16x32_bf16 v[92:95], v[92:95], v[166:169], 0
	v_mfma_f32_16x16x32_bf16 v[110:113], v[102:105], v[174:177], v[92:95]
	v_mfma_f32_16x16x32_bf16 v[98:101], v[102:105], v[170:173], v[96:99]
	s_nop 5
	ds_read_b128 v[90:93], v207 offset:2560
	ds_read_b128 v[102:105], v207 offset:2624
	s_waitcnt lgkmcnt(1)
	v_mfma_f32_16x16x32_bf16 v[94:97], v[90:93], v[114:117], 0
	v_mfma_f32_16x16x32_bf16 v[90:93], v[90:93], v[166:169], 0
	s_waitcnt lgkmcnt(0)
	v_mfma_f32_16x16x32_bf16 v[106:109], v[102:105], v[174:177], v[90:93]
	v_mfma_f32_16x16x32_bf16 v[118:121], v[102:105], v[170:173], v[94:97]
	s_nop 4
	ds_read_b128 v[90:93], v207 offset:5120
	s_waitcnt lgkmcnt(0)
	v_mfma_f32_16x16x32_bf16 v[94:97], v[90:93], v[114:117], 0
	v_mfma_f32_16x16x32_bf16 v[102:105], v[90:93], v[166:169], 0
	v_mfma_f32_16x16x32_bf16 v[90:93], v[178:181], v[170:173], v[94:97]
	s_nop 5
	ds_read_b128 v[94:97], v207 offset:7680
	s_waitcnt lgkmcnt(0)
	v_mfma_f32_16x16x32_bf16 v[114:117], v[94:97], v[114:117], 0
	v_mfma_f32_16x16x32_bf16 v[94:97], v[94:97], v[166:169], 0
	ds_read_b128 v[166:169], v207 offset:7744
	v_mfma_f32_16x16x32_bf16 v[102:105], v[178:181], v[174:177], v[102:105]
	s_waitcnt lgkmcnt(0)
	v_mfma_f32_16x16x32_bf16 v[114:117], v[166:169], v[170:173], v[114:117]
	v_mfma_f32_16x16x32_bf16 v[94:97], v[166:169], v[174:177], v[94:97]
	v_add_u32_e32 v246, v222, v232
	v_add_u32_e32 v245, 63, v246
	v_add_u32_e32 v244, 62, v246
	v_add_u32_e32 v243, 61, v246
	v_add_u32_e32 v241, 60, v246
	v_add_u32_e32 v240, 47, v246
	v_add_u32_e32 v239, 46, v246
	v_add_u32_e32 v238, 45, v246
	v_add_u32_e32 v237, 44, v246
	v_add_u32_e32 v188, 31, v246
	v_add_u32_e32 v186, 30, v246
	v_add_u32_e32 v184, 29, v246
	v_add_u32_e32 v182, 28, v246
	s_and_saveexec_b64 s[12:13], s[4:5]
	s_xor_b64 s[20:21], exec, s[12:13]
	s_cbranch_execz .LBB0_540
	s_cbranch_vccz .Lb1a_q1
; __device__ __forceinline__ float fmax3(float a, float b, float c) { float r; asm("v_max3_f32 %0, %1, %2, %3" : "=v"(r) : "v"(a), "v"(b), "v"(c)); return r; }
; template <int DQK, int DV, int MODE> ...
;     ...
;             float mx = -1e30f;
; #pragma unroll
;             for (int t = 0; t < 4; ++t)
; #pragma unroll
;               for (int r = 0; r < 4; ++r) {
;                 const int j = kt * 64 + t * 16 + fq * 4 + r;
;                 float sx = S[qq][t][r] * c1;
;                 if (MODE == 1) {
;                   const int dist = qpos0 + qrow - j;
;                   sx += bias_lds[min(max(dist, 0), 2047)];
;                   if (need_mask && dist < 0) sx = -1e30f;
;                 } else if (MODE == 2) {
;                   if ((qpos0 + qrow - j) < 0) sx = -1e30f;
;                 } else {
;                   const int rel = 128 + qrow - j;
;                   sx += bias_lds[min(max(rel, 0), 128)];
;                   if (rel < 0 || rel > 128 || j < jmin) sx = -1e30f;
;                 }
;                 P[t][r] = sx;
;               }
; #pragma unroll
;             for (int t = 0; t < 4; ++t) { mx = fmax3(mx, P[t][0], P[t][1]); mx = fmax3(mx, P[t][2], P[t][3]); }
;             mx = xmax_rows(mx);
;             mn = fmax3(mrow[qi], mx, mx);
; #pragma unroll
;             for (int t = 0; t < 4; ++t) P[t] = P[t] - mn;
	v_med3_i32 v165, v245, 0, v198
	v_med3_i32 v166, v244, 0, v198
	v_med3_i32 v167, v243, 0, v198
	v_med3_i32 v168, v241, 0, v198
	v_med3_i32 v169, v240, 0, v198
	v_med3_i32 v170, v239, 0, v198
	v_med3_i32 v171, v238, 0, v198
	v_med3_i32 v172, v237, 0, v198
	v_lshl_add_u32 v165, v165, 2, 0
	v_lshl_add_u32 v166, v166, 2, 0
	v_lshl_add_u32 v167, v167, 2, 0
	v_lshl_add_u32 v168, v168, 2, 0
	v_lshl_add_u32 v169, v169, 2, 0
	v_lshl_add_u32 v170, v170, 2, 0
	v_lshl_add_u32 v171, v171, 2, 0
	v_lshl_add_u32 v172, v172, 2, 0
	ds_read_b32 v165, v165 offset:34816
	ds_read_b32 v166, v166 offset:34816
	ds_read_b32 v167, v167 offset:34816
	ds_read_b32 v168, v168 offset:34816
	ds_read_b32 v169, v169 offset:34816
	ds_read_b32 v170, v170 offset:34816
	ds_read_b32 v171, v171 offset:34816
	ds_read_b32 v172, v172 offset:34816
	v_cmp_gt_i32_e64 s[12:13], 0, v245
	s_waitcnt lgkmcnt(7)
	v_fmac_f32_e32 v165, 0x3e38aa3b, v98
	s_and_b64 s[12:13], vcc, s[12:13]
	v_cndmask_b32_e64 v98, v165, v194, s[12:13]
	v_cmp_gt_i32_e64 s[12:13], 0, v244
	s_waitcnt lgkmcnt(6)
	v_fmac_f32_e32 v166, 0x3e38aa3b, v99
	s_and_b64 s[12:13], vcc, s[12:13]
	v_cndmask_b32_e64 v99, v166, v194, s[12:13]
	v_cmp_gt_i32_e64 s[12:13], 0, v243
	s_waitcnt lgkmcnt(5)
	v_fmac_f32_e32 v167, 0x3e38aa3b, v100
	s_and_b64 s[12:13], vcc, s[12:13]
	v_cndmask_b32_e64 v100, v167, v194, s[12:13]
	v_cmp_gt_i32_e64 s[12:13], 0, v241
	s_waitcnt lgkmcnt(4)
	v_fmac_f32_e32 v168, 0x3e38aa3b, v101
	s_and_b64 s[12:13], vcc, s[12:13]
	v_cndmask_b32_e64 v101, v168, v194, s[12:13]
	v_cmp_gt_i32_e64 s[12:13], 0, v240
	s_waitcnt lgkmcnt(3)
	v_fmac_f32_e32 v169, 0x3e38aa3b, v118
	s_and_b64 s[12:13], vcc, s[12:13]
	v_cndmask_b32_e64 v118, v169, v194, s[12:13]
	v_cmp_gt_i32_e64 s[12:13], 0, v239
	s_waitcnt lgkmcnt(2)
	v_fmac_f32_e32 v170, 0x3e38aa3b, v119
	s_and_b64 s[12:13], vcc, s[12:13]
	v_cndmask_b32_e64 v119, v170, v194, s[12:13]
	v_cmp_gt_i32_e64 s[12:13], 0, v238
	s_waitcnt lgkmcnt(1)
	v_fmac_f32_e32 v171, 0x3e38aa3b, v120
	s_and_b64 s[12:13], vcc, s[12:13]
	v_cndmask_b32_e64 v120, v171, v194, s[12:13]
	v_cmp_gt_i32_e64 s[12:13], 0, v237
	s_waitcnt lgkmcnt(0)
	v_fmac_f32_e32 v172, 0x3e38aa3b, v121
	s_and_b64 s[12:13], vcc, s[12:13]
	v_add_u32_e32 v169, 15, v246
	v_add_u32_e32 v171, 14, v246
	v_add_u32_e32 v173, 13, v246
	v_add_u32_e32 v175, 12, v246
	v_cndmask_b32_e64 v121, v172, v194, s[12:13]
	v_med3_i32 v165, v188, 0, v198
	v_med3_i32 v166, v186, 0, v198
	v_med3_i32 v167, v184, 0, v198
	v_med3_i32 v168, v182, 0, v198
	v_med3_i32 v170, v169, 0, v198
	v_med3_i32 v172, v171, 0, v198
	v_med3_i32 v174, v173, 0, v198
	v_med3_i32 v176, v175, 0, v198
	v_lshl_add_u32 v165, v165, 2, 0
	v_lshl_add_u32 v166, v166, 2, 0
	v_lshl_add_u32 v167, v167, 2, 0
	v_lshl_add_u32 v168, v168, 2, 0
	v_lshl_add_u32 v170, v170, 2, 0
	v_lshl_add_u32 v172, v172, 2, 0
	v_lshl_add_u32 v174, v174, 2, 0
	v_lshl_add_u32 v176, v176, 2, 0
	ds_read_b32 v165, v165 offset:34816
	ds_read_b32 v166, v166 offset:34816
	ds_read_b32 v167, v167 offset:34816
	ds_read_b32 v168, v168 offset:34816
	ds_read_b32 v170, v170 offset:34816
	ds_read_b32 v172, v172 offset:34816
	ds_read_b32 v174, v174 offset:34816
	ds_read_b32 v176, v176 offset:34816
	v_cmp_gt_i32_e64 s[12:13], 0, v188
	s_waitcnt lgkmcnt(7)
	v_fmac_f32_e32 v165, 0x3e38aa3b, v90
	s_and_b64 s[12:13], vcc, s[12:13]
	v_cndmask_b32_e64 v90, v165, v194, s[12:13]
	v_cmp_gt_i32_e64 s[12:13], 0, v186
	s_waitcnt lgkmcnt(6)
	v_fmac_f32_e32 v166, 0x3e38aa3b, v91
	s_and_b64 s[12:13], vcc, s[12:13]
	v_cndmask_b32_e64 v91, v166, v194, s[12:13]
	v_cmp_gt_i32_e64 s[12:13], 0, v184
	s_waitcnt lgkmcnt(5)
	v_fmac_f32_e32 v167, 0x3e38aa3b, v92
	s_and_b64 s[12:13], vcc, s[12:13]
	v_cndmask_b32_e64 v92, v167, v194, s[12:13]
	v_cmp_gt_i32_e64 s[12:13], 0, v182
	s_waitcnt lgkmcnt(4)
	v_fmac_f32_e32 v168, 0x3e38aa3b, v93
	s_and_b64 s[12:13], vcc, s[12:13]
	v_cndmask_b32_e64 v93, v168, v194, s[12:13]
	v_cmp_gt_i32_e64 s[12:13], 0, v169
	s_waitcnt lgkmcnt(3)
	v_fmac_f32_e32 v170, 0x3e38aa3b, v114
	s_and_b64 s[12:13], vcc, s[12:13]
	v_max3_f32 v165, v194, v98, v99
	v_cndmask_b32_e64 v114, v170, v194, s[12:13]
	v_cmp_gt_i32_e64 s[12:13], 0, v171
	v_max3_f32 v165, v165, v100, v101
	s_waitcnt lgkmcnt(2)
	v_fmac_f32_e32 v172, 0x3e38aa3b, v115
	s_and_b64 s[12:13], vcc, s[12:13]
	v_max3_f32 v165, v165, v118, v119
	v_cndmask_b32_e64 v115, v172, v194, s[12:13]
	v_cmp_gt_i32_e64 s[12:13], 0, v173
	v_max3_f32 v165, v165, v120, v121
	s_waitcnt lgkmcnt(1)
	v_fmac_f32_e32 v174, 0x3e38aa3b, v116
	s_and_b64 s[12:13], vcc, s[12:13]
	v_max3_f32 v165, v165, v90, v91
	v_cndmask_b32_e64 v116, v174, v194, s[12:13]
	v_cmp_gt_i32_e64 s[12:13], 0, v175
	v_max3_f32 v165, v165, v92, v93
	s_waitcnt lgkmcnt(0)
	v_fmac_f32_e32 v176, 0x3e38aa3b, v117
	s_and_b64 s[12:13], vcc, s[12:13]
	v_max3_f32 v165, v165, v114, v115
	v_cndmask_b32_e64 v117, v176, v194, s[12:13]
	v_max3_f32 v165, v165, v116, v117
	s_nop 0
	v_mov_b32_e32 v166, v165
	s_nop 1
	v_permlane16_swap_b32_e32 v165, v166
	v_max3_f32 v165, v165, v166, v166
	s_nop 0
	v_mov_b32_e32 v166, v165
	s_nop 1
	v_permlane32_swap_b32_e32 v165, v166
	v_max3_f32 v165, v165, v166, v166
	s_nop 0
	v_max3_f32 v165, v236, v165, v165
	s_nop 0
	v_sub_f32_e32 v176, v98, v165
	v_sub_f32_e32 v177, v99, v165
	v_sub_f32_e32 v172, v100, v165
	v_sub_f32_e32 v173, v101, v165
	v_sub_f32_e32 v166, v118, v165
	v_sub_f32_e32 v167, v119, v165
	v_sub_f32_e32 v174, v120, v165
	v_sub_f32_e32 v175, v121, v165
	v_sub_f32_e32 v170, v90, v165
	v_sub_f32_e32 v171, v91, v165
	v_sub_f32_e32 v180, v92, v165
	v_sub_f32_e32 v181, v93, v165
	v_sub_f32_e32 v178, v114, v165
	v_sub_f32_e32 v179, v115, v165
	v_sub_f32_e32 v168, v116, v165
	v_sub_f32_e32 v169, v117, v165

; __device__ __forceinline__ unsigned pack2(float lo, float hi) { unsigned r; asm("v_cvt_pk_bf16_f32 %0, %1, %2" : "=v"(r) : "v"(lo), "v"(hi)); return r; }
; __device__ __forceinline__ float fexp2(float x) { return __builtin_amdgcn_exp2f(x); }
; __device__ __forceinline__ float fmax3(float a, float b, float c) { float r; asm("v_max3_f32 %0, %1, %2, %3" : "=v"(r) : "v"(a), "v"(b), "v"(c)); return r; }
; template <int DQK, int DV, int MODE> ...
;     ...
;             float mx = -1e30f;
; #pragma unroll
;             for (int t = 0; t < 4; ++t)
; #pragma unroll
;               for (int r = 0; r < 4; ++r) {
;                 const int j = kt * 64 + t * 16 + fq * 4 + r;
;                 float sx = S[qq][t][r] * c1;
;                 if (MODE == 1) {
;                   const int dist = qpos0 + qrow - j;
;                   sx += bias_lds[min(max(dist, 0), 2047)];
;                   if (need_mask && dist < 0) sx = -1e30f;
;                 } else if (MODE == 2) {
;                   if ((qpos0 + qrow - j) < 0) sx = -1e30f;
;                 } else {
;                   const int rel = 128 + qrow - j;
;                   sx += bias_lds[min(max(rel, 0), 128)];
;                   if (rel < 0 || rel > 128 || j < jmin) sx = -1e30f;
;                 }
;                 P[t][r] = sx;
;               }
; #pragma unroll
;             for (int t = 0; t < 4; ++t) { mx = fmax3(mx, P[t][0], P[t][1]); mx = fmax3(mx, P[t][2], P[t][3]); }
;             mx = xmax_rows(mx);
;             mn = fmax3(mrow[qi], mx, mx);
; #pragma unroll
;             for (int t = 0; t < 4; ++t) P[t] = P[t] - mn;
;     ...
; #pragma unroll
;           for (int t = 0; t < 4; ++t) {
; #pragma unroll
;             for (int r = 0; r < 4; ++r) P[t][r] = fexp2(P[t][r]);
;             ls4 += P[t];
;           }
;           lrow[qi] += (ls4[0] + ls4[1]) + (ls4[2] + ls4[3]);
; #pragma unroll
;           for (int s2 = 0; s2 < 2; ++s2) {
;             u32x4 pk;
;             pk.x = pack2(P[2 * s2][0], P[2 * s2][1]); pk.y = pack2(P[2 * s2][2], P[2 * s2][3]);
;             pk.z = pack2(P[2 * s2 + 1][0], P[2 * s2 + 1][1]); pk.w = pack2(P[2 * s2 + 1][2], P[2 * s2 + 1][3]);
;             pf[qq][s2] = __builtin_bit_cast(bf16x8, pk);
;           }
.LBB0_542:
	s_or_b64 exec, exec, s[12:13]
	v_exp_f32_e32 v176, v176
	v_exp_f32_e32 v177, v177
	v_exp_f32_e32 v172, v172
	v_exp_f32_e32 v173, v173
	v_exp_f32_e32 v166, v166
	v_exp_f32_e32 v167, v167
	v_exp_f32_e32 v174, v174
	v_exp_f32_e32 v175, v175
	v_exp_f32_e32 v170, v170
	v_exp_f32_e32 v171, v171
	v_exp_f32_e32 v120, v180
	v_exp_f32_e32 v121, v181
	v_exp_f32_e32 v118, v178
	v_exp_f32_e32 v119, v179
	v_exp_f32_e32 v168, v168
	v_exp_f32_e32 v169, v169
	v_cvt_pk_bf16_f32 v98, v176, v177
	v_cvt_pk_bf16_f32 v99, v172, v173
	v_cvt_pk_bf16_f32 v100, v166, v167
	v_cvt_pk_bf16_f32 v101, v174, v175
	v_cvt_pk_bf16_f32 v90, v170, v171
	v_cvt_pk_bf16_f32 v91, v120, v121
	v_cvt_pk_bf16_f32 v92, v118, v119
	v_cvt_pk_bf16_f32 v93, v168, v169
	s_and_saveexec_b64 s[12:13], s[4:5]
	s_xor_b64 s[4:5], exec, s[12:13]
	s_cbranch_execz .LBB0_544
	s_cbranch_vccz .Lb1a_q2
	v_add_u32_e32 v114, 0x4f, v246
	v_med3_i32 v115, v114, 0, v198
	v_lshl_add_u32 v115, v115, 2, 0
	ds_read_b32 v115, v115 offset:34816
	v_cmp_gt_i32_e64 s[12:13], 0, v114
	s_and_b64 s[12:13], vcc, s[12:13]
	v_add_u32_e32 v114, 0x4e, v246
	s_waitcnt lgkmcnt(0)
	v_fmac_f32_e32 v115, 0x3e38aa3b, v110
	v_cndmask_b32_e64 v110, v115, v194, s[12:13]
	v_med3_i32 v115, v114, 0, v198
	v_lshl_add_u32 v115, v115, 2, 0
	ds_read_b32 v115, v115 offset:34816
	v_cmp_gt_i32_e64 s[12:13], 0, v114
	s_and_b64 s[12:13], vcc, s[12:13]
	v_add_u32_e32 v114, 0x4d, v246
	s_waitcnt lgkmcnt(0)
	v_fmac_f32_e32 v115, 0x3e38aa3b, v111
	v_cndmask_b32_e64 v111, v115, v194, s[12:13]
	v_med3_i32 v115, v114, 0, v198
	v_lshl_add_u32 v115, v115, 2, 0
	ds_read_b32 v115, v115 offset:34816
	v_cmp_gt_i32_e64 s[12:13], 0, v114
	s_and_b64 s[12:13], vcc, s[12:13]
	v_add_u32_e32 v114, 0x4c, v246
	s_waitcnt lgkmcnt(0)
	v_fmac_f32_e32 v115, 0x3e38aa3b, v112
	v_cndmask_b32_e64 v112, v115, v194, s[12:13]
	v_med3_i32 v115, v114, 0, v198
	v_lshl_add_u32 v115, v115, 2, 0
	ds_read_b32 v115, v115 offset:34816
	v_cmp_gt_i32_e64 s[12:13], 0, v114
	v_med3_i32 v114, v245, 0, v198
	v_lshl_add_u32 v114, v114, 2, 0
	ds_read_b32 v114, v114 offset:34816
	s_waitcnt lgkmcnt(1)
	v_fmac_f32_e32 v115, 0x3e38aa3b, v113
	s_and_b64 s[12:13], vcc, s[12:13]
	v_cndmask_b32_e64 v113, v115, v194, s[12:13]
	v_cmp_gt_i32_e64 s[12:13], 0, v245
	s_waitcnt lgkmcnt(0)
	v_fmac_f32_e32 v114, 0x3e38aa3b, v106
	s_and_b64 s[12:13], vcc, s[12:13]
	v_cndmask_b32_e64 v106, v114, v194, s[12:13]
	v_med3_i32 v114, v244, 0, v198
	v_lshl_add_u32 v114, v114, 2, 0
	ds_read_b32 v114, v114 offset:34816
	v_cmp_gt_i32_e64 s[12:13], 0, v244
	s_and_b64 s[12:13], vcc, s[12:13]
	s_waitcnt lgkmcnt(0)
	v_fmac_f32_e32 v114, 0x3e38aa3b, v107
	v_cndmask_b32_e64 v107, v114, v194, s[12:13]
	v_med3_i32 v114, v243, 0, v198
	v_lshl_add_u32 v114, v114, 2, 0
	ds_read_b32 v114, v114 offset:34816
	v_cmp_gt_i32_e64 s[12:13], 0, v243
	s_and_b64 s[12:13], vcc, s[12:13]
	s_waitcnt lgkmcnt(0)
	v_fmac_f32_e32 v114, 0x3e38aa3b, v108
	v_cndmask_b32_e64 v108, v114, v194, s[12:13]
	v_med3_i32 v114, v241, 0, v198
	v_lshl_add_u32 v114, v114, 2, 0
	ds_read_b32 v114, v114 offset:34816
	v_cmp_gt_i32_e64 s[12:13], 0, v241
	s_and_b64 s[12:13], vcc, s[12:13]
	s_waitcnt lgkmcnt(0)
	v_fmac_f32_e32 v114, 0x3e38aa3b, v109
	v_cndmask_b32_e64 v109, v114, v194, s[12:13]
	v_med3_i32 v114, v240, 0, v198
	v_lshl_add_u32 v114, v114, 2, 0
	ds_read_b32 v114, v114 offset:34816
	v_cmp_gt_i32_e64 s[12:13], 0, v240
	s_and_b64 s[12:13], vcc, s[12:13]
	s_waitcnt lgkmcnt(0)
	v_fmac_f32_e32 v114, 0x3e38aa3b, v102
	v_cndmask_b32_e64 v102, v114, v194, s[12:13]
	v_med3_i32 v114, v239, 0, v198
	v_lshl_add_u32 v114, v114, 2, 0
	ds_read_b32 v114, v114 offset:34816
	v_cmp_gt_i32_e64 s[12:13], 0, v239
	s_and_b64 s[12:13], vcc, s[12:13]
	s_waitcnt lgkmcnt(0)
	v_fmac_f32_e32 v114, 0x3e38aa3b, v103
	v_cndmask_b32_e64 v103, v114, v194, s[12:13]
	v_med3_i32 v114, v238, 0, v198
	v_lshl_add_u32 v114, v114, 2, 0
	ds_read_b32 v114, v114 offset:34816
	v_cmp_gt_i32_e64 s[12:13], 0, v238
	s_and_b64 s[12:13], vcc, s[12:13]
	s_waitcnt lgkmcnt(0)
	v_fmac_f32_e32 v114, 0x3e38aa3b, v104
	v_cndmask_b32_e64 v104, v114, v194, s[12:13]
	v_med3_i32 v114, v237, 0, v198
	v_lshl_add_u32 v114, v114, 2, 0
	ds_read_b32 v114, v114 offset:34816
	v_cmp_gt_i32_e64 s[12:13], 0, v237
	s_and_b64 s[12:13], vcc, s[12:13]
	s_waitcnt lgkmcnt(0)
	v_fmac_f32_e32 v114, 0x3e38aa3b, v105
	v_cndmask_b32_e64 v105, v114, v194, s[12:13]
	v_med3_i32 v114, v188, 0, v198
	v_lshl_add_u32 v114, v114, 2, 0
	ds_read_b32 v114, v114 offset:34816
	v_cmp_gt_i32_e64 s[12:13], 0, v188
	s_and_b64 s[12:13], vcc, s[12:13]
	s_waitcnt lgkmcnt(0)
	v_fmac_f32_e32 v114, 0x3e38aa3b, v94
	v_cndmask_b32_e64 v94, v114, v194, s[12:13]
	v_med3_i32 v114, v186, 0, v198
	v_lshl_add_u32 v114, v114, 2, 0
	ds_read_b32 v114, v114 offset:34816
	v_cmp_gt_i32_e64 s[12:13], 0, v186
	s_and_b64 s[12:13], vcc, s[12:13]
	s_waitcnt lgkmcnt(0)
	v_fmac_f32_e32 v114, 0x3e38aa3b, v95
	v_cndmask_b32_e64 v95, v114, v194, s[12:13]
	v_med3_i32 v114, v184, 0, v198
	v_lshl_add_u32 v114, v114, 2, 0
	ds_read_b32 v114, v114 offset:34816
	v_cmp_gt_i32_e64 s[12:13], 0, v184
	s_and_b64 s[12:13], vcc, s[12:13]
	s_waitcnt lgkmcnt(0)
	v_fmac_f32_e32 v114, 0x3e38aa3b, v96
	v_cndmask_b32_e64 v96, v114, v194, s[12:13]
	v_med3_i32 v114, v182, 0, v198
	v_lshl_add_u32 v114, v114, 2, 0
	ds_read_b32 v114, v114 offset:34816
	v_cmp_gt_i32_e64 s[12:13], 0, v182
	s_and_b64 vcc, vcc, s[12:13]
	s_waitcnt lgkmcnt(0)
	v_fmac_f32_e32 v114, 0x3e38aa3b, v97
	v_cndmask_b32_e32 v97, v114, v194, vcc
	v_max3_f32 v114, v194, v110, v111
	s_nop 0
	v_max3_f32 v114, v114, v112, v113
	s_nop 0
	v_max3_f32 v114, v114, v106, v107
	s_nop 0
	v_max3_f32 v114, v114, v108, v109
	s_nop 0
	v_max3_f32 v114, v114, v102, v103
	s_nop 0
	v_max3_f32 v114, v114, v104, v105
	s_nop 0
	v_max3_f32 v114, v114, v94, v95
	s_nop 0
	v_max3_f32 v114, v114, v96, v97
	s_nop 0
	v_mov_b32_e32 v115, v114
	s_nop 1
	v_permlane16_swap_b32_e32 v114, v115
	v_max3_f32 v114, v114, v115, v115
	s_nop 0
	v_mov_b32_e32 v115, v114
	s_nop 1
	v_permlane32_swap_b32_e32 v114, v115
	v_max3_f32 v114, v114, v115, v115
	s_nop 0
	v_max3_f32 v247, v234, v114, v114
	s_nop 0
	v_sub_f32_e32 v188, v110, v247
	v_sub_f32_e32 v189, v111, v247
	v_sub_f32_e32 v186, v112, v247
	v_sub_f32_e32 v187, v113, v247
	v_sub_f32_e32 v184, v106, v247
	v_sub_f32_e32 v185, v107, v247
	v_sub_f32_e32 v182, v108, v247
	v_sub_f32_e32 v183, v109, v247
	v_sub_f32_e32 v180, v102, v247
	v_sub_f32_e32 v181, v103, v247
	v_sub_f32_e32 v178, v104, v247
	v_sub_f32_e32 v179, v105, v247
	v_sub_f32_e32 v117, v97, v247
	v_sub_f32_e32 v116, v96, v247
	v_sub_f32_e32 v115, v95, v247
	v_sub_f32_e32 v114, v94, v247

; __device__ __forceinline__ unsigned pack2(float lo, float hi) { unsigned r; asm("v_cvt_pk_bf16_f32 %0, %1, %2" : "=v"(r) : "v"(lo), "v"(hi)); return r; }
; __device__ __forceinline__ f32x4 mfma16(bf16x8 a, bf16x8 b, f32x4 c) { return __builtin_amdgcn_mfma_f32_16x16x32_bf16(a, b, c, 0, 0, 0); }
; __device__ __forceinline__ float fexp2(float x) { return __builtin_amdgcn_exp2f(x); }
; #define ATT_SCHED_BARRIER __builtin_amdgcn_sched_barrier(0)
; template <int DQK, int DV, int MODE> ...
;     ...
;             const float alpha = fexp2(mrow[qi] - mn);
;             lrow[qi] *= alpha;
; #pragma unroll
;             for (int dt = 0; dt < NDT; ++dt) O[qi][dt] *= alpha;
;           }
;           mrow[qi] = mn;
;           f32x4 ls4 = (f32x4){0.f, 0.f, 0.f, 0.f};
; #pragma unroll
;           for (int t = 0; t < 4; ++t) {
; #pragma unroll
;             for (int r = 0; r < 4; ++r) P[t][r] = fexp2(P[t][r]);
;             ls4 += P[t];
;           }
;           lrow[qi] += (ls4[0] + ls4[1]) + (ls4[2] + ls4[3]);
; #pragma unroll
;           for (int s2 = 0; s2 < 2; ++s2) {
;             u32x4 pk;
;             pk.x = pack2(P[2 * s2][0], P[2 * s2][1]); pk.y = pack2(P[2 * s2][2], P[2 * s2][3]);
;             pk.z = pack2(P[2 * s2 + 1][0], P[2 * s2 + 1][1]); pk.w = pack2(P[2 * s2 + 1][2], P[2 * s2 + 1][3]);
;             pf[qq][s2] = __builtin_bit_cast(bf16x8, pk);
;           }
;     ...
; #pragma unroll
;         for (int s2 = 0; s2 < 2; ++s2)
; #pragma unroll
;           for (int dt = 0; dt < NDT; ++dt) {
;             const bf16x8 vf = *(const bf16x8*)(Vt + (dt * 16 + fr) * VTS + s2 * 32 + fq * 8);
; #pragma unroll
;             for (int qq = 0; qq < QG; ++qq) O[q0 + qq][dt] = mfma16(vf, pf[qq][s2], O[q0 + qq][dt]);
;             if ((dt & (ATT_PVB - 1)) == (ATT_PVB - 1)) ATT_SCHED_BARRIER;
.LBB0_546:
	s_or_b64 exec, exec, s[4:5]
	v_sub_f32_e32 v94, v236, v165
	v_exp_f32_e32 v94, v94
	v_pk_add_f32 v[96:97], v[176:177], 0 op_sel_hi:[1,0]
	v_pk_add_f32 v[102:103], v[172:173], 0 op_sel_hi:[1,0]
	v_pk_add_f32 v[96:97], v[166:167], v[96:97]
	v_pk_add_f32 v[102:103], v[174:175], v[102:103]
	v_pk_add_f32 v[96:97], v[170:171], v[96:97]
	v_pk_add_f32 v[102:103], v[120:121], v[102:103]
	v_pk_add_f32 v[96:97], v[118:119], v[96:97]
	v_pk_add_f32 v[102:103], v[168:169], v[102:103]
	v_mul_f32_e32 v88, v88, v94
	v_mul_f32_e32 v89, v89, v94
	v_mul_f32_e32 v86, v86, v94
	v_mul_f32_e32 v87, v87, v94
	v_mul_f32_e32 v84, v84, v94
	v_mul_f32_e32 v85, v85, v94
	v_mul_f32_e32 v82, v82, v94
	v_mul_f32_e32 v83, v83, v94
	v_mul_f32_e32 v80, v80, v94
	v_mul_f32_e32 v81, v81, v94
	v_mul_f32_e32 v78, v78, v94
	v_mul_f32_e32 v79, v79, v94
	v_mul_f32_e32 v76, v76, v94
	v_mul_f32_e32 v77, v77, v94
	v_mul_f32_e32 v74, v74, v94
	v_mul_f32_e32 v75, v75, v94
	v_mul_f32_e32 v72, v72, v94
	v_mul_f32_e32 v73, v73, v94
	v_mul_f32_e32 v70, v70, v94
	v_mul_f32_e32 v71, v71, v94
	v_mul_f32_e32 v68, v68, v94
	v_mul_f32_e32 v69, v69, v94
	v_mul_f32_e32 v66, v66, v94
	v_mul_f32_e32 v67, v67, v94
	v_mul_f32_e32 v64, v64, v94
	v_mul_f32_e32 v65, v65, v94
	v_mul_f32_e32 v62, v62, v94
	v_mul_f32_e32 v63, v63, v94
	v_mul_f32_e32 v60, v60, v94
	v_mul_f32_e32 v61, v61, v94
	v_mul_f32_e32 v58, v58, v94
	v_mul_f32_e32 v59, v59, v94
	v_add_f32_e32 v95, v96, v97
	v_add_f32_e32 v97, v102, v103
	v_add_f32_e32 v166, v95, v97
	v_fmac_f32_e32 v166, v235, v94
	v_exp_f32_e32 v94, v188
	v_exp_f32_e32 v95, v189
	v_exp_f32_e32 v102, v186
	v_exp_f32_e32 v103, v187
	v_exp_f32_e32 v104, v184
	v_exp_f32_e32 v106, v182
	v_exp_f32_e32 v107, v183
	v_exp_f32_e32 v105, v185
	v_exp_f32_e32 v112, v180
	v_exp_f32_e32 v113, v181
	v_exp_f32_e32 v118, v178
	v_exp_f32_e32 v119, v179
	v_exp_f32_e32 v114, v114
	v_exp_f32_e32 v116, v116
	v_exp_f32_e32 v117, v117
	v_exp_f32_e32 v115, v115
	v_pk_add_f32 v[108:109], v[94:95], 0 op_sel_hi:[1,0]
	v_pk_add_f32 v[110:111], v[102:103], 0 op_sel_hi:[1,0]
	v_sub_f32_e32 v96, v234, v247
	v_pk_add_f32 v[110:111], v[106:107], v[110:111]
	v_pk_add_f32 v[108:109], v[104:105], v[108:109]
	v_exp_f32_e32 v96, v96
	v_pk_add_f32 v[108:109], v[112:113], v[108:109]
	v_pk_add_f32 v[110:111], v[118:119], v[110:111]
	v_pk_add_f32 v[108:109], v[114:115], v[108:109]
	v_pk_add_f32 v[110:111], v[116:117], v[110:111]
	v_mul_f32_e32 v56, v56, v96
	v_mul_f32_e32 v57, v57, v96
	v_pk_mov_b32 v[120:121], v[108:109], v[110:111] op_sel:[1,0]
	v_mov_b32_e32 v109, v111
	v_pk_add_f32 v[108:109], v[120:121], v[108:109]
	v_mul_f32_e32 v54, v54, v96
	v_mul_f32_e32 v55, v55, v96
	v_mul_f32_e32 v52, v52, v96
	v_mul_f32_e32 v53, v53, v96
	v_mul_f32_e32 v50, v50, v96
	v_mul_f32_e32 v51, v51, v96
	v_mul_f32_e32 v48, v48, v96
	v_mul_f32_e32 v49, v49, v96
	v_mul_f32_e32 v46, v46, v96
	v_mul_f32_e32 v47, v47, v96
	v_mul_f32_e32 v44, v44, v96
	v_mul_f32_e32 v45, v45, v96
	v_mul_f32_e32 v42, v42, v96
	v_mul_f32_e32 v43, v43, v96
	v_mul_f32_e32 v40, v40, v96
	v_mul_f32_e32 v41, v41, v96
	v_mul_f32_e32 v38, v38, v96
	v_mul_f32_e32 v39, v39, v96
	v_mul_f32_e32 v36, v36, v96
	v_mul_f32_e32 v37, v37, v96
	v_mul_f32_e32 v34, v34, v96
	v_mul_f32_e32 v35, v35, v96
	v_mul_f32_e32 v24, v24, v96
	v_mul_f32_e32 v25, v25, v96
	v_mul_f32_e32 v22, v22, v96
	v_mul_f32_e32 v23, v23, v96
	v_mul_f32_e32 v12, v12, v96
	v_mul_f32_e32 v13, v13, v96
	v_mul_f32_e32 v10, v10, v96
	v_mul_f32_e32 v11, v11, v96
	v_add_f32_e32 v110, v108, v109
	v_fmac_f32_e32 v110, v233, v96
	v_cvt_pk_bf16_f32 v94, v94, v95
	v_cvt_pk_bf16_f32 v95, v102, v103
	v_cvt_pk_bf16_f32 v96, v104, v105
	v_cvt_pk_bf16_f32 v97, v106, v107
	v_cvt_pk_bf16_f32 v102, v112, v113
	v_cvt_pk_bf16_f32 v103, v118, v119
	v_cvt_pk_bf16_f32 v104, v114, v115
	v_cvt_pk_bf16_f32 v105, v116, v117
	ds_read_b128 v[106:109], v208 offset:14336
	ds_read_b128 v[114:117], v208 offset:16896
	ds_read_b128 v[118:121], v208 offset:19456
	ds_read_b128 v[170:173], v208 offset:22016
	ds_read_b128 v[174:177], v208 offset:24576
	ds_read_b128 v[178:181], v208 offset:27136
	ds_read_b128 v[182:185], v208 offset:29696
	ds_read_b128 v[186:189], v208 offset:32256
	s_waitcnt lgkmcnt(7)
; __device__ __forceinline__ f32x4 mfma16(bf16x8 a, bf16x8 b, f32x4 c) { return __builtin_amdgcn_mfma_f32_16x16x32_bf16(a, b, c, 0, 0, 0); }
; #define ATT_SCHED_BARRIER __builtin_amdgcn_sched_barrier(0)
; template <int DQK, int DV, int MODE> ...
;     ...
; #pragma unroll
;         for (int s2 = 0; s2 < 2; ++s2)
; #pragma unroll
;           for (int dt = 0; dt < NDT; ++dt) {
;             const bf16x8 vf = *(const bf16x8*)(Vt + (dt * 16 + fr) * VTS + s2 * 32 + fq * 8);
; #pragma unroll
;             for (int qq = 0; qq < QG; ++qq) O[q0 + qq][dt] = mfma16(vf, pf[qq][s2], O[q0 + qq][dt]);
;             if ((dt & (ATT_PVB - 1)) == (ATT_PVB - 1)) ATT_SCHED_BARRIER;
;           }
	v_mfma_f32_16x16x32_bf16 v[86:89], v[106:109], v[98:101], v[86:89]
	v_mfma_f32_16x16x32_bf16 v[54:57], v[106:109], v[94:97], v[54:57]
	ds_read_b128 v[106:109], v208 offset:14400
	s_waitcnt lgkmcnt(7)
	v_mfma_f32_16x16x32_bf16 v[82:85], v[114:117], v[98:101], v[82:85]
	v_mfma_f32_16x16x32_bf16 v[50:53], v[114:117], v[94:97], v[50:53]
	ds_read_b128 v[114:117], v208 offset:16960
	s_waitcnt lgkmcnt(7)
	v_mfma_f32_16x16x32_bf16 v[78:81], v[118:121], v[98:101], v[78:81]
	v_mfma_f32_16x16x32_bf16 v[46:49], v[118:121], v[94:97], v[46:49]
	ds_read_b128 v[118:121], v208 offset:19520
	s_waitcnt lgkmcnt(7)
	v_mfma_f32_16x16x32_bf16 v[74:77], v[170:173], v[98:101], v[74:77]
	v_mfma_f32_16x16x32_bf16 v[42:45], v[170:173], v[94:97], v[42:45]
	ds_read_b128 v[170:173], v208 offset:22080
	s_waitcnt lgkmcnt(7)
	v_mfma_f32_16x16x32_bf16 v[70:73], v[174:177], v[98:101], v[70:73]
	v_mfma_f32_16x16x32_bf16 v[38:41], v[174:177], v[94:97], v[38:41]
	ds_read_b128 v[174:177], v208 offset:24640
	s_waitcnt lgkmcnt(7)
	v_mfma_f32_16x16x32_bf16 v[66:69], v[178:181], v[98:101], v[66:69]
	v_mfma_f32_16x16x32_bf16 v[34:37], v[178:181], v[94:97], v[34:37]
	ds_read_b128 v[178:181], v208 offset:27200
	s_waitcnt lgkmcnt(7)
	v_mfma_f32_16x16x32_bf16 v[62:65], v[182:185], v[98:101], v[62:65]
	v_mfma_f32_16x16x32_bf16 v[22:25], v[182:185], v[94:97], v[22:25]
	ds_read_b128 v[182:185], v208 offset:29760
	s_waitcnt lgkmcnt(7)
	v_mfma_f32_16x16x32_bf16 v[58:61], v[186:189], v[98:101], v[58:61]
	v_mfma_f32_16x16x32_bf16 v[10:13], v[186:189], v[94:97], v[10:13]
	ds_read_b128 v[186:189], v208 offset:32320
	s_waitcnt lgkmcnt(7)
	v_mfma_f32_16x16x32_bf16 v[86:89], v[106:109], v[90:93], v[86:89]
	v_mfma_f32_16x16x32_bf16 v[54:57], v[106:109], v[102:105], v[54:57]
	s_waitcnt lgkmcnt(6)
	v_mfma_f32_16x16x32_bf16 v[82:85], v[114:117], v[90:93], v[82:85]
	v_mfma_f32_16x16x32_bf16 v[50:53], v[114:117], v[102:105], v[50:53]
	s_waitcnt lgkmcnt(5)
	v_mfma_f32_16x16x32_bf16 v[78:81], v[118:121], v[90:93], v[78:81]
	v_mfma_f32_16x16x32_bf16 v[46:49], v[118:121], v[102:105], v[46:49]
	s_waitcnt lgkmcnt(4)
	v_mfma_f32_16x16x32_bf16 v[74:77], v[170:173], v[90:93], v[74:77]
	v_mfma_f32_16x16x32_bf16 v[42:45], v[170:173], v[102:105], v[42:45]
	s_waitcnt lgkmcnt(3)
	v_mfma_f32_16x16x32_bf16 v[70:73], v[174:177], v[90:93], v[70:73]
	v_mfma_f32_16x16x32_bf16 v[38:41], v[174:177], v[102:105], v[38:41]
	s_waitcnt lgkmcnt(2)
	v_mfma_f32_16x16x32_bf16 v[66:69], v[178:181], v[90:93], v[66:69]
	v_mfma_f32_16x16x32_bf16 v[34:37], v[178:181], v[102:105], v[34:37]
	s_waitcnt lgkmcnt(1)
	v_mfma_f32_16x16x32_bf16 v[62:65], v[182:185], v[90:93], v[62:65]
	v_mfma_f32_16x16x32_bf16 v[22:25], v[182:185], v[102:105], v[22:25]
	s_waitcnt lgkmcnt(0)
	v_mfma_f32_16x16x32_bf16 v[58:61], v[186:189], v[90:93], v[58:61]
	v_mfma_f32_16x16x32_bf16 v[10:13], v[186:189], v[102:105], v[10:13]
	v_mov_b32_e32 v236, v165
	v_mov_b32_e32 v234, v247
	v_mov_b32_e32 v235, v166
	v_mov_b32_e32 v233, v110

; __device__ __forceinline__ float fmax3(float a, float b, float c) { float r; asm("v_max3_f32 %0, %1, %2, %3" : "=v"(r) : "v"(a), "v"(b), "v"(c)); return r; }
; template <int DQK, int DV, int MODE> ...
;     ...
;             float mx = -1e30f;
; #pragma unroll
;             for (int t = 0; t < 4; ++t)
; #pragma unroll
;               for (int r = 0; r < 4; ++r) {
;                 const int j = kt * 64 + t * 16 + fq * 4 + r;
;                 float sx = S[qq][t][r] * c1;
;                 if (MODE == 1) {
;                   const int dist = qpos0 + qrow - j;
;                   sx += bias_lds[min(max(dist, 0), 2047)];
;                   if (need_mask && dist < 0) sx = -1e30f;
;                 } else if (MODE == 2) {
;                   if ((qpos0 + qrow - j) < 0) sx = -1e30f;
;                 } else {
;                   const int rel = 128 + qrow - j;
;                   sx += bias_lds[min(max(rel, 0), 128)];
;                   if (rel < 0 || rel > 128 || j < jmin) sx = -1e30f;
;                 }
;                 P[t][r] = sx;
;               }
; #pragma unroll
;             for (int t = 0; t < 4; ++t) { mx = fmax3(mx, P[t][0], P[t][1]); mx = fmax3(mx, P[t][2], P[t][3]); }
;             mx = xmax_rows(mx);
;             mn = fmax3(mrow[qi], mx, mx);
; #pragma unroll
;             for (int t = 0; t < 4; ++t) P[t] = P[t] - mn;
.Lb1a_q1:
	v_lshlrev_b32_e32 v238, 2, v246
	v_add_u32_e32 v238, 0x8800, v238
	ds_read2_b32 v[176:177], v238 offset0:63 offset1:62
	ds_read2_b32 v[172:173], v238 offset0:61 offset1:60
	ds_read2_b32 v[166:167], v238 offset0:47 offset1:46
	ds_read2_b32 v[174:175], v238 offset0:45 offset1:44
	ds_read2_b32 v[170:171], v238 offset0:31 offset1:30
	ds_read2_b32 v[180:181], v238 offset0:29 offset1:28
	ds_read2_b32 v[178:179], v238 offset0:15 offset1:14
	ds_read2_b32 v[168:169], v238 offset0:13 offset1:12
	s_waitcnt lgkmcnt(7)
	v_fmac_f32_e32 v176, 0x3e38aa3b, v98
	v_fmac_f32_e32 v177, 0x3e38aa3b, v99
	s_waitcnt lgkmcnt(6)
	v_fmac_f32_e32 v172, 0x3e38aa3b, v100
	v_fmac_f32_e32 v173, 0x3e38aa3b, v101
	s_waitcnt lgkmcnt(5)
	v_fmac_f32_e32 v166, 0x3e38aa3b, v118
	v_fmac_f32_e32 v167, 0x3e38aa3b, v119
	s_waitcnt lgkmcnt(4)
	v_fmac_f32_e32 v174, 0x3e38aa3b, v120
	v_fmac_f32_e32 v175, 0x3e38aa3b, v121
	s_waitcnt lgkmcnt(3)
	v_fmac_f32_e32 v170, 0x3e38aa3b, v90
	v_fmac_f32_e32 v171, 0x3e38aa3b, v91
	s_waitcnt lgkmcnt(2)
	v_fmac_f32_e32 v180, 0x3e38aa3b, v92
	v_fmac_f32_e32 v181, 0x3e38aa3b, v93
	s_waitcnt lgkmcnt(1)
	v_fmac_f32_e32 v178, 0x3e38aa3b, v114
	v_fmac_f32_e32 v179, 0x3e38aa3b, v115
	s_waitcnt lgkmcnt(0)
	v_fmac_f32_e32 v168, 0x3e38aa3b, v116
	v_fmac_f32_e32 v169, 0x3e38aa3b, v117
	v_max3_f32 v165, v176, v177, v172
	v_max3_f32 v165, v165, v173, v166
	v_max3_f32 v165, v165, v167, v174
	v_max3_f32 v165, v165, v175, v170
	v_max3_f32 v165, v165, v171, v180
	v_max3_f32 v165, v165, v181, v178
	v_max3_f32 v165, v165, v179, v168
	v_max3_f32 v165, v165, v169, v165
	v_mov_b32_e32 v237, v165
	s_nop 1
	v_permlane16_swap_b32_e32 v165, v237
	v_max3_f32 v165, v165, v237, v237
	v_mov_b32_e32 v237, v165
	s_nop 1
	v_permlane32_swap_b32_e32 v165, v237
	v_max3_f32 v165, v165, v237, v237
	s_nop 0
	v_max3_f32 v165, v236, v165, v165
	s_nop 0
	v_sub_f32_e32 v176, v176, v165
	v_sub_f32_e32 v177, v177, v165
	v_sub_f32_e32 v172, v172, v165
	v_sub_f32_e32 v173, v173, v165
	v_sub_f32_e32 v166, v166, v165
	v_sub_f32_e32 v167, v167, v165
	v_sub_f32_e32 v174, v174, v165
	v_sub_f32_e32 v175, v175, v165
	v_sub_f32_e32 v170, v170, v165
	v_sub_f32_e32 v171, v171, v165
	v_sub_f32_e32 v180, v180, v165
	v_sub_f32_e32 v181, v181, v165
	v_sub_f32_e32 v178, v178, v165
	v_sub_f32_e32 v179, v179, v165
	v_sub_f32_e32 v168, v168, v165
	v_sub_f32_e32 v169, v169, v165
	s_branch .LBB0_540
.Lb1a_q2:
	ds_read2_b32 v[188:189], v238 offset0:79 offset1:78
	ds_read2_b32 v[186:187], v238 offset0:77 offset1:76
	ds_read2_b32 v[184:185], v238 offset0:63 offset1:62
	ds_read2_b32 v[182:183], v238 offset0:61 offset1:60
	ds_read2_b32 v[180:181], v238 offset0:47 offset1:46
	ds_read2_b32 v[178:179], v238 offset0:45 offset1:44
	ds_read2_b32 v[114:115], v238 offset0:31 offset1:30
	ds_read2_b32 v[116:117], v238 offset0:29 offset1:28
	s_waitcnt lgkmcnt(7)
	v_fmac_f32_e32 v188, 0x3e38aa3b, v110
	v_fmac_f32_e32 v189, 0x3e38aa3b, v111
	s_waitcnt lgkmcnt(6)
	v_fmac_f32_e32 v186, 0x3e38aa3b, v112
	v_fmac_f32_e32 v187, 0x3e38aa3b, v113
	s_waitcnt lgkmcnt(5)
	v_fmac_f32_e32 v184, 0x3e38aa3b, v106
	v_fmac_f32_e32 v185, 0x3e38aa3b, v107
	s_waitcnt lgkmcnt(4)
	v_fmac_f32_e32 v182, 0x3e38aa3b, v108
	v_fmac_f32_e32 v183, 0x3e38aa3b, v109
	s_waitcnt lgkmcnt(3)
	v_fmac_f32_e32 v180, 0x3e38aa3b, v102
	v_fmac_f32_e32 v181, 0x3e38aa3b, v103
	s_waitcnt lgkmcnt(2)
	v_fmac_f32_e32 v178, 0x3e38aa3b, v104
	v_fmac_f32_e32 v179, 0x3e38aa3b, v105
	s_waitcnt lgkmcnt(1)
	v_fmac_f32_e32 v114, 0x3e38aa3b, v94
	v_fmac_f32_e32 v115, 0x3e38aa3b, v95
	s_waitcnt lgkmcnt(0)
	v_fmac_f32_e32 v116, 0x3e38aa3b, v96
	v_fmac_f32_e32 v117, 0x3e38aa3b, v97
	v_max3_f32 v247, v188, v189, v186
	v_max3_f32 v247, v247, v187, v184
	v_max3_f32 v247, v247, v185, v182
	v_max3_f32 v247, v247, v183, v180
	v_max3_f32 v247, v247, v181, v178
	v_max3_f32 v247, v247, v179, v114
	v_max3_f32 v247, v247, v115, v116
	v_max3_f32 v247, v247, v117, v247
	v_mov_b32_e32 v237, v247
	s_nop 1
	v_permlane16_swap_b32_e32 v247, v237
	v_max3_f32 v247, v247, v237, v237
	v_mov_b32_e32 v237, v247
	s_nop 1
	v_permlane32_swap_b32_e32 v247, v237
	v_max3_f32 v247, v247, v237, v237
	s_nop 0
	v_max3_f32 v247, v234, v247, v247
	s_nop 0
	v_sub_f32_e32 v188, v188, v247
	v_sub_f32_e32 v189, v189, v247
	v_sub_f32_e32 v186, v186, v247
	v_sub_f32_e32 v187, v187, v247
	v_sub_f32_e32 v184, v184, v247
	v_sub_f32_e32 v185, v185, v247
	v_sub_f32_e32 v182, v182, v247
	v_sub_f32_e32 v183, v183, v247
	v_sub_f32_e32 v180, v180, v247
	v_sub_f32_e32 v181, v181, v247
	v_sub_f32_e32 v178, v178, v247
	v_sub_f32_e32 v179, v179, v247
	v_sub_f32_e32 v114, v114, v247
	v_sub_f32_e32 v115, v115, v247
	v_sub_f32_e32 v116, v116, v247
	v_sub_f32_e32 v117, v117, v247
	s_branch .LBB0_544
